# hand-written gdn_k2 chunk loop (LDS fragment reads pipelined 6 deep, saddr loads, one top-of-chunk wait), dead nb<256 gdn_k2 copy removed
# speedup vs baseline: 1.1033x; 1.0277x over previous
.LBB0_409:
	s_andn2_b64 vcc, exec, s[0:1]
	s_cbranch_vccnz .LBB0_357
	s_branch .LBB0_357

.LBB0_470:
	s_and_b64 vcc, exec, s[0:1]
	s_cbranch_vccz .LBB0_474
	s_and_b32 s46, s52, 1
	s_lshr_b32 s47, s52, 1
	s_and_b32 s44, s47, 3
	s_lshr_b32 s45, s47, 2
	v_and_b32_e32 v250, 63, v144
	v_lshrrev_b32_e32 v251, 6, v144
	v_and_b32_e32 v252, 15, v250
	v_lshrrev_b32_e32 v253, 4, v250
	v_lshl_add_u32 v0, v251, 4, v252
	s_lshl_b32 s47, s46, 6
	v_add_u32_e32 v0, s47, v0
	v_lshlrev_b32_e32 v248, 3, v253
	v_mov_b32_e32 v249, v248
	s_movk_i32 s47, 272
	v_mad_u32_u24 v248, v252, s47, v248
	s_movk_i32 s47, 144
	v_mad_u32_u24 v249, v252, s47, v249
	v_lshlrev_b32_e32 v250, 2, v253
	v_add_u32_e32 v251, 0x400, v0
	v_lshlrev_b32_e32 v251, 1, v251
	v_lshlrev_b32_e32 v252, 1, v0
	s_movk_i32 s47, 3072
	v_add_u32_e32 v253, 0, v250
	v_mad_u32_u24 v210, v253, s47, v251
	v_lshl_add_u32 v226, v253, 13, v252
	v_add_u32_e32 v253, 1, v250
	v_mad_u32_u24 v211, v253, s47, v251
	v_lshl_add_u32 v227, v253, 13, v252
	v_add_u32_e32 v253, 2, v250
	v_mad_u32_u24 v212, v253, s47, v251
	v_lshl_add_u32 v228, v253, 13, v252
	v_add_u32_e32 v253, 3, v250
	v_mad_u32_u24 v213, v253, s47, v251
	v_lshl_add_u32 v229, v253, 13, v252
	v_add_u32_e32 v253, 16, v250
	v_mad_u32_u24 v214, v253, s47, v251
	v_lshl_add_u32 v230, v253, 13, v252
	v_add_u32_e32 v253, 17, v250
	v_mad_u32_u24 v215, v253, s47, v251
	v_lshl_add_u32 v231, v253, 13, v252
	v_add_u32_e32 v253, 18, v250
	v_mad_u32_u24 v216, v253, s47, v251
	v_lshl_add_u32 v232, v253, 13, v252
	v_add_u32_e32 v253, 19, v250
	v_mad_u32_u24 v217, v253, s47, v251
	v_lshl_add_u32 v233, v253, 13, v252
	v_add_u32_e32 v253, 32, v250
	v_mad_u32_u24 v218, v253, s47, v251
	v_lshl_add_u32 v234, v253, 13, v252
	v_add_u32_e32 v253, 33, v250
	v_mad_u32_u24 v219, v253, s47, v251
	v_lshl_add_u32 v235, v253, 13, v252
	v_add_u32_e32 v253, 34, v250
	v_mad_u32_u24 v220, v253, s47, v251
	v_lshl_add_u32 v236, v253, 13, v252
	v_add_u32_e32 v253, 35, v250
	v_mad_u32_u24 v221, v253, s47, v251
	v_lshl_add_u32 v237, v253, 13, v252
	v_add_u32_e32 v253, 48, v250
	v_mad_u32_u24 v222, v253, s47, v251
	v_lshl_add_u32 v242, v253, 13, v252
	v_add_u32_e32 v253, 49, v250
	v_mad_u32_u24 v223, v253, s47, v251
	v_lshl_add_u32 v243, v253, 13, v252
	v_add_u32_e32 v253, 50, v250
	v_mad_u32_u24 v224, v253, s47, v251
	v_lshl_add_u32 v244, v253, 13, v252
	v_add_u32_e32 v253, 51, v250
	v_mad_u32_u24 v225, v253, s47, v251
	v_lshl_add_u32 v245, v253, 13, v252
	v_mov_b32_e32 v142, v0
	v_mov_b32_e32 v143, v250
	v_lshrrev_b32_e32 v250, 4, v144
	v_and_b32_e32 v251, 15, v144
	v_lshlrev_b32_e32 v251, 4, v251
	s_movk_i32 s47, 3072
	v_add_u32_e32 v252, 0, v250
	v_mad_u32_u24 v200, v252, s47, v251
	v_add_u32_e32 v252, 16, v250
	v_mad_u32_u24 v201, v252, s47, v251
	v_add_u32_e32 v252, 32, v250
	v_mad_u32_u24 v202, v252, s47, v251
	v_add_u32_e32 v252, 48, v250
	v_mad_u32_u24 v203, v252, s47, v251
	s_movk_i32 s47, 272
	v_mad_u32_u24 v246, v250, s47, v251
	v_lshlrev_b32_e32 v252, 4, v144
	v_add_u32_e32 v204, 8192, v252
	v_add_u32_e32 v205, 12288, v252
	v_add_u32_e32 v206, 16384, v252
	v_add_u32_e32 v207, 20480, v252
	v_mov_b32_e32 v208, v252
	v_add_u32_e32 v209, 4096, v252
	v_lshrrev_b32_e32 v250, 3, v144
	v_and_b32_e32 v251, 7, v144
	v_lshlrev_b32_e32 v251, 4, v251
	s_movk_i32 s47, 144
	v_mad_u32_u24 v247, v250, s47, v251
	s_mul_i32 s47, s45, 0x600000
	s_lshl_b32 s48, s44, 8
	s_add_u32 s47, s47, s48
	s_add_u32 s47, s47, 0xc440000
	s_add_u32 s4, s26, s47
	s_addc_u32 s5, s27, 0
	s_lshl_b32 s47, s45, 2
	s_add_u32 s47, s47, s44
	s_mul_i32 s48, s47, 0xc0000
	s_add_u32 s38, s24, s48
	s_addc_u32 s39, s25, 0
	s_lshl_b32 s48, s47, 7
	s_add_u32 s48, s48, 0xf854000
	s_add_u32 s42, s26, s48
	s_addc_u32 s43, s27, 0
	s_lshl_b32 s47, s45, 24
	s_lshl_b32 s48, s44, 8
	s_add_u32 s47, s47, s48
	s_add_u32 s47, s47, 0x3c40600
	s_add_u32 s40, s26, s47
	s_addc_u32 s41, s27, 0
	s_barrier
	global_load_dwordx4 v[66:69], v200, s[4:5] offset:1024
	global_load_dwordx4 v[82:85], v200, s[4:5]
	global_load_dwordx4 v[106:109], v204, s[38:39]
	global_load_dwordx4 v[70:73], v201, s[4:5] offset:1024
	global_load_dwordx4 v[86:89], v201, s[4:5]
	global_load_dwordx4 v[110:113], v205, s[38:39]
	global_load_dwordx4 v[74:77], v202, s[4:5] offset:1024
	global_load_dwordx4 v[90:93], v202, s[4:5]
	global_load_dwordx4 v[114:117], v206, s[38:39]
	global_load_dwordx4 v[78:81], v203, s[4:5] offset:1024
	global_load_dwordx4 v[94:97], v203, s[4:5]
	global_load_dwordx4 v[118:121], v207, s[38:39]
	global_load_dwordx4 v[98:101], v208, s[38:39]
	global_load_dwordx4 v[102:105], v209, s[38:39]
	global_load_ushort v126, v210, s[4:5]
	global_load_ushort v127, v211, s[4:5]
	global_load_ushort v128, v212, s[4:5]
	global_load_ushort v129, v213, s[4:5]
	global_load_ushort v130, v214, s[4:5]
	global_load_ushort v131, v215, s[4:5]
	global_load_ushort v132, v216, s[4:5]
	global_load_ushort v133, v217, s[4:5]
	global_load_ushort v134, v218, s[4:5]
	global_load_ushort v135, v219, s[4:5]
	global_load_ushort v136, v220, s[4:5]
	global_load_ushort v137, v221, s[4:5]
	global_load_ushort v138, v222, s[4:5]
	global_load_ushort v139, v223, s[4:5]
	global_load_ushort v140, v224, s[4:5]
	global_load_ushort v141, v225, s[4:5]
	s_add_u32 s4, s4, 0x30000
	s_addc_u32 s5, s5, 0
	s_add_u32 s38, s38, 0x6000
	s_addc_u32 s39, s39, 0
	v_mov_b32_e32 v2, 0
	v_mov_b32_e32 v3, 0
	v_mov_b32_e32 v4, 0
	v_mov_b32_e32 v5, 0
	v_mov_b32_e32 v6, 0
	v_mov_b32_e32 v7, 0
	v_mov_b32_e32 v8, 0
	v_mov_b32_e32 v9, 0
	v_mov_b32_e32 v10, 0
	v_mov_b32_e32 v11, 0
	v_mov_b32_e32 v12, 0
	v_mov_b32_e32 v13, 0
	v_mov_b32_e32 v14, 0
	v_mov_b32_e32 v15, 0
	v_mov_b32_e32 v16, 0
	v_mov_b32_e32 v17, 0
	v_mov_b32_e32 v18, 0
	v_mov_b32_e32 v19, 0
	v_mov_b32_e32 v20, 0
	v_mov_b32_e32 v21, 0
	v_mov_b32_e32 v22, 0
	v_mov_b32_e32 v23, 0
	v_mov_b32_e32 v24, 0
	v_mov_b32_e32 v25, 0
	v_mov_b32_e32 v26, 0
	v_mov_b32_e32 v27, 0
	v_mov_b32_e32 v28, 0
	v_mov_b32_e32 v29, 0
	v_mov_b32_e32 v30, 0
	v_mov_b32_e32 v31, 0
	v_mov_b32_e32 v32, 0
	v_mov_b32_e32 v33, 0
	s_mov_b32 s2, 0
	s_waitcnt vmcnt(0)
.Lk2_chunk:
	s_waitcnt vmcnt(16)
	ds_write_b128 v246, v[66:69]
	ds_write_b128 v246, v[82:85] offset:17408
	ds_write_b128 v247, v[106:109] offset:44032
	ds_write_b128 v246, v[70:73] offset:4352
	ds_write_b128 v246, v[86:89] offset:21760
	ds_write_b128 v247, v[110:113] offset:48640
	ds_write_b128 v246, v[74:77] offset:8704
	ds_write_b128 v246, v[90:93] offset:26112
	ds_write_b128 v247, v[114:117] offset:53248
	ds_write_b128 v246, v[78:81] offset:13056
	ds_write_b128 v246, v[94:97] offset:30464
	ds_write_b128 v247, v[118:121] offset:57856
	ds_write_b128 v247, v[98:101] offset:34816
	ds_write_b128 v247, v[102:105] offset:39424
	v_lshlrev_b32_e32 v34, 16, v126
	v_mov_b32_e32 v50, 0
	v_lshlrev_b32_e32 v35, 16, v127
	v_mov_b32_e32 v51, 0
	v_lshlrev_b32_e32 v36, 16, v128
	v_mov_b32_e32 v52, 0
	v_lshlrev_b32_e32 v37, 16, v129
	v_mov_b32_e32 v53, 0
	v_lshlrev_b32_e32 v38, 16, v130
	v_mov_b32_e32 v54, 0
	v_lshlrev_b32_e32 v39, 16, v131
	v_mov_b32_e32 v55, 0
	v_lshlrev_b32_e32 v40, 16, v132
	v_mov_b32_e32 v56, 0
	v_lshlrev_b32_e32 v41, 16, v133
	v_mov_b32_e32 v57, 0
	v_lshlrev_b32_e32 v42, 16, v134
	v_mov_b32_e32 v58, 0
	v_lshlrev_b32_e32 v43, 16, v135
	v_mov_b32_e32 v59, 0
	v_lshlrev_b32_e32 v44, 16, v136
	v_mov_b32_e32 v60, 0
	v_lshlrev_b32_e32 v45, 16, v137
	v_mov_b32_e32 v61, 0
	v_lshlrev_b32_e32 v46, 16, v138
	v_mov_b32_e32 v62, 0
	v_lshlrev_b32_e32 v47, 16, v139
	v_mov_b32_e32 v63, 0
	v_lshlrev_b32_e32 v48, 16, v140
	v_mov_b32_e32 v64, 0
	v_lshlrev_b32_e32 v49, 16, v141
	v_mov_b32_e32 v65, 0
	s_waitcnt lgkmcnt(0)
	s_barrier
	global_load_dword v254, v1, s[42:43]
	s_add_u32 s42, s42, 4
	s_addc_u32 s43, s43, 0
	s_cmpk_eq_u32 s2, 31
	s_cbranch_scc1 .Lk2_nold
	global_load_dwordx4 v[66:69], v200, s[4:5] offset:1024
	global_load_dwordx4 v[82:85], v200, s[4:5]
	global_load_dwordx4 v[106:109], v204, s[38:39]
	global_load_dwordx4 v[70:73], v201, s[4:5] offset:1024
	global_load_dwordx4 v[86:89], v201, s[4:5]
	global_load_dwordx4 v[110:113], v205, s[38:39]
	global_load_dwordx4 v[74:77], v202, s[4:5] offset:1024
	global_load_dwordx4 v[90:93], v202, s[4:5]
	global_load_dwordx4 v[114:117], v206, s[38:39]
	global_load_dwordx4 v[78:81], v203, s[4:5] offset:1024
	global_load_dwordx4 v[94:97], v203, s[4:5]
	global_load_dwordx4 v[118:121], v207, s[38:39]
	global_load_dwordx4 v[98:101], v208, s[38:39]
	global_load_dwordx4 v[102:105], v209, s[38:39]
	global_load_ushort v126, v210, s[4:5]
	global_load_ushort v127, v211, s[4:5]
	global_load_ushort v128, v212, s[4:5]
	global_load_ushort v129, v213, s[4:5]
	global_load_ushort v130, v214, s[4:5]
	global_load_ushort v131, v215, s[4:5]
	global_load_ushort v132, v216, s[4:5]
	global_load_ushort v133, v217, s[4:5]
	global_load_ushort v134, v218, s[4:5]
	global_load_ushort v135, v219, s[4:5]
	global_load_ushort v136, v220, s[4:5]
	global_load_ushort v137, v221, s[4:5]
	global_load_ushort v138, v222, s[4:5]
	global_load_ushort v139, v223, s[4:5]
	global_load_ushort v140, v224, s[4:5]
	global_load_ushort v141, v225, s[4:5]
	s_add_u32 s4, s4, 0x30000
	s_addc_u32 s5, s5, 0
	s_add_u32 s38, s38, 0x6000
	s_addc_u32 s39, s39, 0
.Lk2_nold:
	ds_read_b64 v[164:165], v248 offset:0
	ds_read_b64 v[166:167], v248 offset:32
	ds_read_b64 v[168:169], v248 offset:17408
	ds_read_b64 v[170:171], v248 offset:17440
	ds_read_b64 v[172:173], v248 offset:4352
	ds_read_b64 v[174:175], v248 offset:4384
	ds_read_b64 v[176:177], v248 offset:21760
	ds_read_b64 v[178:179], v248 offset:21792
	ds_read_b64 v[180:181], v248 offset:8704
	ds_read_b64 v[182:183], v248 offset:8736
	ds_read_b64 v[184:185], v248 offset:26112
	ds_read_b64 v[186:187], v248 offset:26144
	ds_read_b64 v[188:189], v248 offset:13056
	ds_read_b64 v[190:191], v248 offset:13088
	v_cvt_pk_bf16_f32 v196, v2, v3
	v_cvt_pk_bf16_f32 v197, v4, v5
	v_cvt_pk_bf16_f32 v198, v6, v7
	v_cvt_pk_bf16_f32 v199, v8, v9
	s_nop 1
	s_waitcnt lgkmcnt(12)
	v_mfma_f32_16x16x32_bf16 v[34:37], v[164:167], v[196:199], v[34:37]
	ds_read_b64 v[192:193], v248 offset:30464
	ds_read_b64 v[194:195], v248 offset:30496
	s_waitcnt lgkmcnt(12)
	v_mfma_f32_16x16x32_bf16 v[50:53], v[168:171], v[196:199], v[50:53]
	ds_read_b64 v[164:165], v248 offset:64
	ds_read_b64 v[166:167], v248 offset:96
	s_waitcnt lgkmcnt(12)
	v_mfma_f32_16x16x32_bf16 v[38:41], v[172:175], v[196:199], v[38:41]
	ds_read_b64 v[168:169], v248 offset:17472
	ds_read_b64 v[170:171], v248 offset:17504
	s_waitcnt lgkmcnt(12)
	v_mfma_f32_16x16x32_bf16 v[54:57], v[176:179], v[196:199], v[54:57]
	ds_read_b64 v[172:173], v248 offset:4416
	ds_read_b64 v[174:175], v248 offset:4448
	s_waitcnt lgkmcnt(12)
	v_mfma_f32_16x16x32_bf16 v[42:45], v[180:183], v[196:199], v[42:45]
	ds_read_b64 v[176:177], v248 offset:21824
	ds_read_b64 v[178:179], v248 offset:21856
	s_waitcnt lgkmcnt(12)
	v_mfma_f32_16x16x32_bf16 v[58:61], v[184:187], v[196:199], v[58:61]
	ds_read_b64 v[180:181], v248 offset:8768
	ds_read_b64 v[182:183], v248 offset:8800
	s_waitcnt lgkmcnt(12)
	v_mfma_f32_16x16x32_bf16 v[46:49], v[188:191], v[196:199], v[46:49]
	ds_read_b64 v[184:185], v248 offset:26176
	ds_read_b64 v[186:187], v248 offset:26208
	s_waitcnt lgkmcnt(12)
	v_mfma_f32_16x16x32_bf16 v[62:65], v[192:195], v[196:199], v[62:65]
	ds_read_b64 v[188:189], v248 offset:13120
	ds_read_b64 v[190:191], v248 offset:13152
	v_cvt_pk_bf16_f32 v196, v10, v11
	v_cvt_pk_bf16_f32 v197, v12, v13
	v_cvt_pk_bf16_f32 v198, v14, v15
	v_cvt_pk_bf16_f32 v199, v16, v17
	s_nop 1
	s_waitcnt lgkmcnt(12)
	v_mfma_f32_16x16x32_bf16 v[34:37], v[164:167], v[196:199], v[34:37]
	ds_read_b64 v[192:193], v248 offset:30528
	ds_read_b64 v[194:195], v248 offset:30560
	s_waitcnt lgkmcnt(12)
	v_mfma_f32_16x16x32_bf16 v[50:53], v[168:171], v[196:199], v[50:53]
	ds_read_b64 v[164:165], v248 offset:128
	ds_read_b64 v[166:167], v248 offset:160
	s_waitcnt lgkmcnt(12)
	v_mfma_f32_16x16x32_bf16 v[38:41], v[172:175], v[196:199], v[38:41]
	ds_read_b64 v[168:169], v248 offset:17536
	ds_read_b64 v[170:171], v248 offset:17568
	s_waitcnt lgkmcnt(12)
	v_mfma_f32_16x16x32_bf16 v[54:57], v[176:179], v[196:199], v[54:57]
	ds_read_b64 v[172:173], v248 offset:4480
	ds_read_b64 v[174:175], v248 offset:4512
	s_waitcnt lgkmcnt(12)
	v_mfma_f32_16x16x32_bf16 v[42:45], v[180:183], v[196:199], v[42:45]
	ds_read_b64 v[176:177], v248 offset:21888
	ds_read_b64 v[178:179], v248 offset:21920
	s_waitcnt lgkmcnt(12)
	v_mfma_f32_16x16x32_bf16 v[58:61], v[184:187], v[196:199], v[58:61]
	ds_read_b64 v[180:181], v248 offset:8832
	ds_read_b64 v[182:183], v248 offset:8864
	s_waitcnt lgkmcnt(12)
	v_mfma_f32_16x16x32_bf16 v[46:49], v[188:191], v[196:199], v[46:49]
	ds_read_b64 v[184:185], v248 offset:26240
	ds_read_b64 v[186:187], v248 offset:26272
	s_waitcnt lgkmcnt(12)
	v_mfma_f32_16x16x32_bf16 v[62:65], v[192:195], v[196:199], v[62:65]
	ds_read_b64 v[188:189], v248 offset:13184
	ds_read_b64 v[190:191], v248 offset:13216
	v_cvt_pk_bf16_f32 v196, v18, v19
	v_cvt_pk_bf16_f32 v197, v20, v21
	v_cvt_pk_bf16_f32 v198, v22, v23
	v_cvt_pk_bf16_f32 v199, v24, v25
	s_nop 1
	s_waitcnt lgkmcnt(12)
	v_mfma_f32_16x16x32_bf16 v[34:37], v[164:167], v[196:199], v[34:37]
	ds_read_b64 v[192:193], v248 offset:30592
	ds_read_b64 v[194:195], v248 offset:30624
	s_waitcnt lgkmcnt(12)
	v_mfma_f32_16x16x32_bf16 v[50:53], v[168:171], v[196:199], v[50:53]
	ds_read_b64 v[164:165], v248 offset:192
	ds_read_b64 v[166:167], v248 offset:224
	s_waitcnt lgkmcnt(12)
	v_mfma_f32_16x16x32_bf16 v[38:41], v[172:175], v[196:199], v[38:41]
	ds_read_b64 v[168:169], v248 offset:17600
	ds_read_b64 v[170:171], v248 offset:17632
	s_waitcnt lgkmcnt(12)
	v_mfma_f32_16x16x32_bf16 v[54:57], v[176:179], v[196:199], v[54:57]
	ds_read_b64 v[172:173], v248 offset:4544
	ds_read_b64 v[174:175], v248 offset:4576
	s_waitcnt lgkmcnt(12)
	v_mfma_f32_16x16x32_bf16 v[42:45], v[180:183], v[196:199], v[42:45]
	ds_read_b64 v[176:177], v248 offset:21952
	ds_read_b64 v[178:179], v248 offset:21984
	s_waitcnt lgkmcnt(12)
	v_mfma_f32_16x16x32_bf16 v[58:61], v[184:187], v[196:199], v[58:61]
	ds_read_b64 v[180:181], v248 offset:8896
	ds_read_b64 v[182:183], v248 offset:8928
	s_waitcnt lgkmcnt(12)
	v_mfma_f32_16x16x32_bf16 v[46:49], v[188:191], v[196:199], v[46:49]
	ds_read_b64 v[184:185], v248 offset:26304
	ds_read_b64 v[186:187], v248 offset:26336
	s_waitcnt lgkmcnt(12)
	v_mfma_f32_16x16x32_bf16 v[62:65], v[192:195], v[196:199], v[62:65]
	ds_read_b64 v[188:189], v248 offset:13248
	ds_read_b64 v[190:191], v248 offset:13280
	v_cvt_pk_bf16_f32 v196, v26, v27
	v_cvt_pk_bf16_f32 v197, v28, v29
	v_cvt_pk_bf16_f32 v198, v30, v31
	v_cvt_pk_bf16_f32 v199, v32, v33
	s_nop 1
	s_waitcnt lgkmcnt(12)
	v_mfma_f32_16x16x32_bf16 v[34:37], v[164:167], v[196:199], v[34:37]
	ds_read_b64 v[192:193], v248 offset:30656
	ds_read_b64 v[194:195], v248 offset:30688
	s_waitcnt lgkmcnt(12)
	v_mfma_f32_16x16x32_bf16 v[50:53], v[168:171], v[196:199], v[50:53]
	ds_read_b64 v[164:165], v249 offset:34816
	ds_read_b64 v[166:167], v249 offset:34848
	s_waitcnt lgkmcnt(12)
	v_mfma_f32_16x16x32_bf16 v[38:41], v[172:175], v[196:199], v[38:41]
	ds_read_b64 v[168:169], v249 offset:37120
	ds_read_b64 v[170:171], v249 offset:37152
	s_waitcnt lgkmcnt(12)
	v_mfma_f32_16x16x32_bf16 v[54:57], v[176:179], v[196:199], v[54:57]
	ds_read_b64 v[172:173], v249 offset:39424
	ds_read_b64 v[174:175], v249 offset:39456
	s_waitcnt lgkmcnt(12)
	v_mfma_f32_16x16x32_bf16 v[42:45], v[180:183], v[196:199], v[42:45]
	ds_read_b64 v[176:177], v249 offset:41728
	ds_read_b64 v[178:179], v249 offset:41760
	s_waitcnt lgkmcnt(12)
	v_mfma_f32_16x16x32_bf16 v[58:61], v[184:187], v[196:199], v[58:61]
	ds_read_b64 v[180:181], v249 offset:44032
	ds_read_b64 v[182:183], v249 offset:44064
	s_waitcnt lgkmcnt(12)
	v_mfma_f32_16x16x32_bf16 v[46:49], v[188:191], v[196:199], v[46:49]
	ds_read_b64 v[184:185], v249 offset:46336
	ds_read_b64 v[186:187], v249 offset:46368
	s_waitcnt lgkmcnt(12)
	v_mfma_f32_16x16x32_bf16 v[62:65], v[192:195], v[196:199], v[62:65]
	ds_read_b64 v[188:189], v249 offset:48640
	ds_read_b64 v[190:191], v249 offset:48672
	s_cmpk_eq_u32 s2, 31
	s_cbranch_scc1 .Lk2_w0
	s_waitcnt vmcnt(30)
	s_branch .Lk2_w1

.Lk2_w1:
	v_mul_f32_e32 v2, v254, v2
	v_mul_f32_e32 v3, v254, v3
	v_mul_f32_e32 v4, v254, v4
	v_mul_f32_e32 v5, v254, v5
	v_mul_f32_e32 v6, v254, v6
	v_mul_f32_e32 v7, v254, v7
	v_mul_f32_e32 v8, v254, v8
	v_mul_f32_e32 v9, v254, v9
	v_mul_f32_e32 v10, v254, v10
	v_mul_f32_e32 v11, v254, v11
	v_mul_f32_e32 v12, v254, v12
	v_mul_f32_e32 v13, v254, v13
	v_mul_f32_e32 v14, v254, v14
	v_mul_f32_e32 v15, v254, v15
	v_mul_f32_e32 v16, v254, v16
	v_mul_f32_e32 v17, v254, v17
	v_mul_f32_e32 v18, v254, v18
	v_mul_f32_e32 v19, v254, v19
	v_mul_f32_e32 v20, v254, v20
	v_mul_f32_e32 v21, v254, v21
	v_mul_f32_e32 v22, v254, v22
	v_mul_f32_e32 v23, v254, v23
	v_mul_f32_e32 v24, v254, v24
	v_mul_f32_e32 v25, v254, v25
	v_mul_f32_e32 v26, v254, v26
	v_mul_f32_e32 v27, v254, v27
	v_mul_f32_e32 v28, v254, v28
	v_mul_f32_e32 v29, v254, v29
	v_mul_f32_e32 v30, v254, v30
	v_mul_f32_e32 v31, v254, v31
	v_mul_f32_e32 v32, v254, v32
	v_mul_f32_e32 v33, v254, v33
	v_cvt_pk_bf16_f32 v196, v34, v35
	v_cvt_pk_bf16_f32 v197, v36, v37
	v_cvt_pk_bf16_f32 v198, v38, v39
	v_cvt_pk_bf16_f32 v199, v40, v41
	s_nop 1
	s_waitcnt lgkmcnt(12)
	v_mfma_f32_16x16x32_bf16 v[50:53], v[164:167], v[196:199], v[50:53]
	ds_read_b64 v[192:193], v249 offset:50944
	ds_read_b64 v[194:195], v249 offset:50976
	s_waitcnt lgkmcnt(12)
	v_mfma_f32_16x16x32_bf16 v[54:57], v[168:171], v[196:199], v[54:57]
	ds_read_b64 v[164:165], v249 offset:53248
	ds_read_b64 v[166:167], v249 offset:53280
	s_waitcnt lgkmcnt(12)
	v_mfma_f32_16x16x32_bf16 v[58:61], v[172:175], v[196:199], v[58:61]
	ds_read_b64 v[168:169], v249 offset:55552
	ds_read_b64 v[170:171], v249 offset:55584
	s_waitcnt lgkmcnt(12)
	v_mfma_f32_16x16x32_bf16 v[62:65], v[176:179], v[196:199], v[62:65]
	ds_read_b64 v[172:173], v249 offset:57856
	ds_read_b64 v[174:175], v249 offset:57888
	s_waitcnt lgkmcnt(12)
	v_mfma_f32_16x16x32_bf16 v[2:5], v[180:183], v[196:199], v[2:5]
	ds_read_b64 v[176:177], v249 offset:60160
	ds_read_b64 v[178:179], v249 offset:60192
	s_waitcnt lgkmcnt(12)
	v_mfma_f32_16x16x32_bf16 v[6:9], v[184:187], v[196:199], v[6:9]
	ds_read_b64 v[180:181], v249 offset:34880
	ds_read_b64 v[182:183], v249 offset:34912
	s_waitcnt lgkmcnt(12)
	v_mfma_f32_16x16x32_bf16 v[10:13], v[188:191], v[196:199], v[10:13]
	ds_read_b64 v[184:185], v249 offset:37184
	ds_read_b64 v[186:187], v249 offset:37216
	s_waitcnt lgkmcnt(12)
	v_mfma_f32_16x16x32_bf16 v[14:17], v[192:195], v[196:199], v[14:17]
	ds_read_b64 v[188:189], v249 offset:39488
	ds_read_b64 v[190:191], v249 offset:39520
	s_waitcnt lgkmcnt(12)
	v_mfma_f32_16x16x32_bf16 v[18:21], v[164:167], v[196:199], v[18:21]
	ds_read_b64 v[192:193], v249 offset:41792
	ds_read_b64 v[194:195], v249 offset:41824
	s_waitcnt lgkmcnt(12)
	v_mfma_f32_16x16x32_bf16 v[22:25], v[168:171], v[196:199], v[22:25]
	ds_read_b64 v[164:165], v249 offset:44096
	ds_read_b64 v[166:167], v249 offset:44128
	s_waitcnt lgkmcnt(12)
	v_mfma_f32_16x16x32_bf16 v[26:29], v[172:175], v[196:199], v[26:29]
	ds_read_b64 v[168:169], v249 offset:46400
	ds_read_b64 v[170:171], v249 offset:46432
	s_waitcnt lgkmcnt(12)
	v_mfma_f32_16x16x32_bf16 v[30:33], v[176:179], v[196:199], v[30:33]
	ds_read_b64 v[172:173], v249 offset:48704
	ds_read_b64 v[174:175], v249 offset:48736
	v_cvt_pk_bf16_f32 v196, v42, v43
	v_cvt_pk_bf16_f32 v197, v44, v45
	v_cvt_pk_bf16_f32 v198, v46, v47
	v_cvt_pk_bf16_f32 v199, v48, v49
	s_nop 1
	s_waitcnt lgkmcnt(12)
	v_mfma_f32_16x16x32_bf16 v[50:53], v[180:183], v[196:199], v[50:53]
	ds_read_b64 v[176:177], v249 offset:51008
	ds_read_b64 v[178:179], v249 offset:51040
	s_waitcnt lgkmcnt(12)
	v_mfma_f32_16x16x32_bf16 v[54:57], v[184:187], v[196:199], v[54:57]
	ds_read_b64 v[180:181], v249 offset:53312
	ds_read_b64 v[182:183], v249 offset:53344
	s_waitcnt lgkmcnt(12)
	v_mfma_f32_16x16x32_bf16 v[58:61], v[188:191], v[196:199], v[58:61]
	ds_read_b64 v[184:185], v249 offset:55616
	ds_read_b64 v[186:187], v249 offset:55648
	s_waitcnt lgkmcnt(12)
	v_mfma_f32_16x16x32_bf16 v[62:65], v[192:195], v[196:199], v[62:65]
	ds_read_b64 v[188:189], v249 offset:57920
	ds_read_b64 v[190:191], v249 offset:57952
	s_waitcnt lgkmcnt(12)
	v_mfma_f32_16x16x32_bf16 v[2:5], v[164:167], v[196:199], v[2:5]
	ds_read_b64 v[192:193], v249 offset:60224
	ds_read_b64 v[194:195], v249 offset:60256
	s_waitcnt lgkmcnt(12)
	v_mfma_f32_16x16x32_bf16 v[6:9], v[168:171], v[196:199], v[6:9]
	s_waitcnt lgkmcnt(10)
	v_mfma_f32_16x16x32_bf16 v[10:13], v[172:175], v[196:199], v[10:13]
	s_waitcnt lgkmcnt(8)
	v_mfma_f32_16x16x32_bf16 v[14:17], v[176:179], v[196:199], v[14:17]
	s_waitcnt lgkmcnt(6)
	v_mfma_f32_16x16x32_bf16 v[18:21], v[180:183], v[196:199], v[18:21]
	s_waitcnt lgkmcnt(4)
	v_mfma_f32_16x16x32_bf16 v[22:25], v[184:187], v[196:199], v[22:25]
	s_waitcnt lgkmcnt(2)
	v_mfma_f32_16x16x32_bf16 v[26:29], v[188:191], v[196:199], v[26:29]
	s_waitcnt lgkmcnt(0)
	v_mfma_f32_16x16x32_bf16 v[30:33], v[192:195], v[196:199], v[30:33]
	s_nop 3
	v_cvt_pk_bf16_f32 v250, v50, v50
	global_store_short v226, v250, s[40:41]
	s_nop 0
	v_cvt_pk_bf16_f32 v250, v51, v51
	global_store_short v227, v250, s[40:41]
	s_nop 0
	v_cvt_pk_bf16_f32 v250, v52, v52
	global_store_short v228, v250, s[40:41]
	s_nop 0
	v_cvt_pk_bf16_f32 v250, v53, v53
	global_store_short v229, v250, s[40:41]
	s_nop 0
	v_cvt_pk_bf16_f32 v250, v54, v54
	global_store_short v230, v250, s[40:41]
	s_nop 0
	v_cvt_pk_bf16_f32 v250, v55, v55
	global_store_short v231, v250, s[40:41]
	s_nop 0
	v_cvt_pk_bf16_f32 v250, v56, v56
	global_store_short v232, v250, s[40:41]
	s_nop 0
	v_cvt_pk_bf16_f32 v250, v57, v57
	global_store_short v233, v250, s[40:41]
	s_nop 0
	v_cvt_pk_bf16_f32 v250, v58, v58
	global_store_short v234, v250, s[40:41]
	s_nop 0
	v_cvt_pk_bf16_f32 v250, v59, v59
	global_store_short v235, v250, s[40:41]
	s_nop 0
	v_cvt_pk_bf16_f32 v250, v60, v60
	global_store_short v236, v250, s[40:41]
	s_nop 0
	v_cvt_pk_bf16_f32 v250, v61, v61
	global_store_short v237, v250, s[40:41]
	s_nop 0
	v_cvt_pk_bf16_f32 v250, v62, v62
	global_store_short v242, v250, s[40:41]
	s_nop 0
	v_cvt_pk_bf16_f32 v250, v63, v63
	global_store_short v243, v250, s[40:41]
	s_nop 0
	v_cvt_pk_bf16_f32 v250, v64, v64
	global_store_short v244, v250, s[40:41]
	s_nop 0
	v_cvt_pk_bf16_f32 v250, v65, v65
	global_store_short v245, v250, s[40:41]
	s_nop 0
	s_add_u32 s40, s40, 0x80000
	s_addc_u32 s41, s41, 0
	s_barrier
	s_add_u32 s2, s2, 1
	s_cmpk_lt_u32 s2, 32
	s_cbranch_scc1 .Lk2_chunk
	v_readlane_b32 s47, v239, 53
	s_lshl_b32 s47, s47, 3
	s_add_u32 s47, s47, s45
	s_lshl_b32 s47, s47, 2
	s_add_u32 s47, s47, s44
	s_lshl_b32 s47, s47, 16
	s_add_u32 s47, s47, 0x4450000
	s_add_u32 s40, s24, s47
	s_addc_u32 s41, s25, 0
	v_lshlrev_b32_e32 v250, 9, v143
	v_lshl_add_u32 v250, v142, 2, v250
	s_nop 7
	global_store_dword v250, v2, s[40:41] offset:0 nt
	global_store_dword v250, v3, s[40:41] offset:512 nt
	global_store_dword v250, v4, s[40:41] offset:1024 nt
	global_store_dword v250, v5, s[40:41] offset:1536 nt
	v_add_u32_e32 v250, 0x2000, v250
	global_store_dword v250, v6, s[40:41] offset:0 nt
	global_store_dword v250, v7, s[40:41] offset:512 nt
	global_store_dword v250, v8, s[40:41] offset:1024 nt
	global_store_dword v250, v9, s[40:41] offset:1536 nt
	v_add_u32_e32 v250, 0x2000, v250
	global_store_dword v250, v10, s[40:41] offset:0 nt
	global_store_dword v250, v11, s[40:41] offset:512 nt
	global_store_dword v250, v12, s[40:41] offset:1024 nt
	global_store_dword v250, v13, s[40:41] offset:1536 nt
	v_add_u32_e32 v250, 0x2000, v250
	global_store_dword v250, v14, s[40:41] offset:0 nt
	global_store_dword v250, v15, s[40:41] offset:512 nt
	global_store_dword v250, v16, s[40:41] offset:1024 nt
	global_store_dword v250, v17, s[40:41] offset:1536 nt
	v_add_u32_e32 v250, 0x2000, v250
	global_store_dword v250, v18, s[40:41] offset:0 nt
	global_store_dword v250, v19, s[40:41] offset:512 nt
	global_store_dword v250, v20, s[40:41] offset:1024 nt
	global_store_dword v250, v21, s[40:41] offset:1536 nt
	v_add_u32_e32 v250, 0x2000, v250
	global_store_dword v250, v22, s[40:41] offset:0 nt
	global_store_dword v250, v23, s[40:41] offset:512 nt
	global_store_dword v250, v24, s[40:41] offset:1024 nt
	global_store_dword v250, v25, s[40:41] offset:1536 nt
	v_add_u32_e32 v250, 0x2000, v250
	global_store_dword v250, v26, s[40:41] offset:0 nt
	global_store_dword v250, v27, s[40:41] offset:512 nt
	global_store_dword v250, v28, s[40:41] offset:1024 nt
	global_store_dword v250, v29, s[40:41] offset:1536 nt
	v_add_u32_e32 v250, 0x2000, v250
	global_store_dword v250, v30, s[40:41] offset:0 nt
	global_store_dword v250, v31, s[40:41] offset:512 nt
	global_store_dword v250, v32, s[40:41] offset:1024 nt
	global_store_dword v250, v33, s[40:41] offset:1536 nt
